# RWKV post loop: a/g loads of a token issued with its other loads (two in-loop load-latency serialisations removed)
# baseline (speedup 1.0000x reference)
.LBB0_1362:
	v_lshl_add_u64 v[60:61], s[8:9], 0, v[92:93]
	v_add_co_u32_e32 v62, vcc, 0x6200000, v60
	s_nop 1
	v_addc_co_u32_e32 v63, vcc, 0, v61, vcc
	global_load_dwordx4 v[88:91], v[62:63], off
	v_add_co_u32_e32 v60, vcc, 0x7200000, v60
	s_nop 1
	v_addc_co_u32_e32 v61, vcc, 0, v61, vcc
	global_load_dwordx4 v[60:63], v[60:61], off
	s_waitcnt vmcnt(4)
	v_cvt_f32_f16_sdwa v97, v80 dst_sel:DWORD dst_unused:UNUSED_PAD src0_sel:WORD_1
	v_cvt_f32_f16_e32 v96, v80
	v_cvt_f32_f16_sdwa v103, v84 dst_sel:DWORD dst_unused:UNUSED_PAD src0_sel:WORD_1
	v_cvt_f32_f16_e32 v102, v84
	s_waitcnt vmcnt(3)
	v_cvt_f32_f16_sdwa v99, v76 dst_sel:DWORD dst_unused:UNUSED_PAD src0_sel:WORD_1
	v_pk_add_f32 v[102:103], v[102:103], v[96:97] neg_lo:[0,1] neg_hi:[0,1]
	v_cvt_f32_f16_e32 v98, v76
	v_pk_fma_f32 v[96:97], v[4:5], v[102:103], v[96:97]
	v_cvt_f32_f16_sdwa v103, v72 dst_sel:DWORD dst_unused:UNUSED_PAD src0_sel:WORD_1
	v_cvt_f32_f16_e32 v102, v72
	v_cvt_f32_f16_e32 v80, v77
	s_add_i32 s11, s11, 8
	s_add_u32 s0, s0, 0xd000
	v_pk_add_f32 v[102:103], v[102:103], v[98:99] neg_lo:[0,1] neg_hi:[0,1]
	s_addc_u32 s1, s1, 0
	v_pk_fma_f32 v[98:99], v[12:13], v[102:103], v[98:99]
	s_add_u32 s4, s4, 0x4000
	s_addc_u32 s5, s5, 0
	s_add_u32 s8, s8, 0x2000
	s_addc_u32 s9, s9, 0
	s_cmp_ge_u32 s11, s10
	s_waitcnt vmcnt(1)
	v_cvt_f32_f16_e32 v100, v88
	v_cvt_f32_f16_sdwa v101, v88 dst_sel:DWORD dst_unused:UNUSED_PAD src0_sel:WORD_1
	v_cvt_f32_f16_e32 v76, v89
	v_cvt_f32_f16_e32 v88, v85
	v_pk_add_f32 v[100:101], v[100:101], -1.0 op_sel_hi:[1,0]
	s_nop 0
	v_pk_fma_f32 v[100:101], v[20:21], v[100:101], 1.0 op_sel_hi:[1,1,0]
	s_nop 0
	v_pk_mul_f32 v[98:99], v[98:99], v[100:101]
	s_nop 0
	v_pk_mul_f32 v[96:97], v[96:97], v[98:99]
	s_nop 0
	v_pk_mul_f32 v[96:97], v[28:29], v[96:97]
	s_nop 0
	v_add_f32_e32 v72, 0, v96
	v_add_f32_e32 v98, v97, v72
	v_cvt_f32_f16_sdwa v97, v81 dst_sel:DWORD dst_unused:UNUSED_PAD src0_sel:WORD_1
	v_cvt_f32_f16_e32 v96, v81
	v_cvt_f32_f16_sdwa v81, v77 dst_sel:DWORD dst_unused:UNUSED_PAD src0_sel:WORD_1
	v_cvt_f32_f16_sdwa v77, v89 dst_sel:DWORD dst_unused:UNUSED_PAD src0_sel:WORD_1
	v_cvt_f32_f16_sdwa v89, v85 dst_sel:DWORD dst_unused:UNUSED_PAD src0_sel:WORD_1
	v_pk_add_f32 v[76:77], v[76:77], -1.0 op_sel_hi:[1,0]
	v_pk_add_f32 v[84:85], v[88:89], v[96:97] neg_lo:[0,1] neg_hi:[0,1]
	v_cvt_f32_f16_sdwa v89, v73 dst_sel:DWORD dst_unused:UNUSED_PAD src0_sel:WORD_1
	v_cvt_f32_f16_e32 v88, v73
	v_pk_fma_f32 v[76:77], v[22:23], v[76:77], 1.0 op_sel_hi:[1,1,0]
	v_pk_fma_f32 v[84:85], v[6:7], v[84:85], v[96:97]
	v_pk_add_f32 v[72:73], v[88:89], v[80:81] neg_lo:[0,1] neg_hi:[0,1]
	s_nop 0
	v_pk_fma_f32 v[72:73], v[14:15], v[72:73], v[80:81]
	v_cvt_f32_f16_e32 v80, v90
	v_pk_mul_f32 v[72:73], v[72:73], v[76:77]
	v_cvt_f32_f16_sdwa v77, v78 dst_sel:DWORD dst_unused:UNUSED_PAD src0_sel:WORD_1
	v_pk_mul_f32 v[72:73], v[84:85], v[72:73]
	v_cvt_f32_f16_sdwa v85, v86 dst_sel:DWORD dst_unused:UNUSED_PAD src0_sel:WORD_1
	v_pk_mul_f32 v[72:73], v[30:31], v[72:73]
	v_cvt_f32_f16_e32 v84, v86
	v_add_f32_e32 v72, v72, v98
	v_add_f32_e32 v88, v73, v72
	v_cvt_f32_f16_sdwa v73, v82 dst_sel:DWORD dst_unused:UNUSED_PAD src0_sel:WORD_1
	v_cvt_f32_f16_e32 v72, v82
	v_cvt_f32_f16_e32 v76, v78
	v_cvt_f32_f16_sdwa v81, v90 dst_sel:DWORD dst_unused:UNUSED_PAD src0_sel:WORD_1
	v_cvt_f32_f16_e32 v78, v91
	v_pk_add_f32 v[84:85], v[84:85], v[72:73] neg_lo:[0,1] neg_hi:[0,1]
	v_pk_add_f32 v[80:81], v[80:81], -1.0 op_sel_hi:[1,0]
	v_pk_fma_f32 v[72:73], v[0:1], v[84:85], v[72:73]
	v_cvt_f32_f16_sdwa v85, v74 dst_sel:DWORD dst_unused:UNUSED_PAD src0_sel:WORD_1
	v_cvt_f32_f16_e32 v84, v74
	v_pk_fma_f32 v[80:81], v[16:17], v[80:81], 1.0 op_sel_hi:[1,1,0]
	v_pk_add_f32 v[84:85], v[84:85], v[76:77] neg_lo:[0,1] neg_hi:[0,1]
	s_nop 0
	v_pk_fma_f32 v[76:77], v[8:9], v[84:85], v[76:77]
	v_cvt_f32_f16_sdwa v85, v67 dst_sel:DWORD dst_unused:UNUSED_PAD src0_sel:WORD_1
	v_pk_mul_f32 v[76:77], v[76:77], v[80:81]
	v_cvt_f32_f16_sdwa v81, v87 dst_sel:DWORD dst_unused:UNUSED_PAD src0_sel:WORD_1
	v_pk_mul_f32 v[72:73], v[72:73], v[76:77]
	v_cvt_f32_f16_e32 v80, v87
	v_pk_mul_f32 v[72:73], v[24:25], v[72:73]
	v_cvt_f32_f16_sdwa v77, v79 dst_sel:DWORD dst_unused:UNUSED_PAD src0_sel:WORD_1
	v_add_f32_e32 v72, v72, v88
	v_add_f32_e32 v82, v73, v72
	v_cvt_f32_f16_sdwa v73, v83 dst_sel:DWORD dst_unused:UNUSED_PAD src0_sel:WORD_1
	v_cvt_f32_f16_e32 v72, v83
	v_cvt_f32_f16_e32 v76, v79
	v_cvt_f32_f16_sdwa v79, v91 dst_sel:DWORD dst_unused:UNUSED_PAD src0_sel:WORD_1
	v_cvt_f32_f16_e32 v84, v67
	v_pk_add_f32 v[80:81], v[80:81], v[72:73] neg_lo:[0,1] neg_hi:[0,1]
	v_cvt_f32_f16_sdwa v67, v71 dst_sel:DWORD dst_unused:UNUSED_PAD src0_sel:WORD_1
	v_pk_fma_f32 v[72:73], v[2:3], v[80:81], v[72:73]
	v_cvt_f32_f16_sdwa v81, v75 dst_sel:DWORD dst_unused:UNUSED_PAD src0_sel:WORD_1
	v_cvt_f32_f16_e32 v80, v75
	s_waitcnt vmcnt(0)
	v_cvt_f32_f16_sdwa v83, v62 dst_sel:DWORD dst_unused:UNUSED_PAD src0_sel:WORD_1
	v_pk_add_f32 v[74:75], v[80:81], v[76:77] neg_lo:[0,1] neg_hi:[0,1]
	s_nop 0
	v_pk_fma_f32 v[74:75], v[10:11], v[74:75], v[76:77]
	v_pk_add_f32 v[76:77], v[78:79], -1.0 op_sel_hi:[1,0]
	v_cvt_f32_f16_sdwa v79, v68 dst_sel:DWORD dst_unused:UNUSED_PAD src0_sel:WORD_1
	v_pk_fma_f32 v[76:77], v[18:19], v[76:77], 1.0 op_sel_hi:[1,1,0]
	v_cvt_f32_f16_e32 v78, v68
	v_pk_mul_f32 v[74:75], v[74:75], v[76:77]
	v_cvt_f32_f16_sdwa v77, v64 dst_sel:DWORD dst_unused:UNUSED_PAD src0_sel:WORD_1
	v_pk_mul_f32 v[72:73], v[72:73], v[74:75]
	v_cvt_f32_f16_e32 v74, v56
	v_cvt_f32_f16_sdwa v75, v56 dst_sel:DWORD dst_unused:UNUSED_PAD src0_sel:WORD_1
	v_cvt_f32_f16_e32 v76, v64
	v_cvt_f32_f16_sdwa v81, v65 dst_sel:DWORD dst_unused:UNUSED_PAD src0_sel:WORD_1
	v_cvt_f32_f16_e32 v80, v65
	v_cvt_f32_f16_sdwa v65, v69 dst_sel:DWORD dst_unused:UNUSED_PAD src0_sel:WORD_1
	v_cvt_f32_f16_e32 v64, v69
	v_cvt_f32_f16_e32 v68, v57
	v_cvt_f32_f16_sdwa v69, v57 dst_sel:DWORD dst_unused:UNUSED_PAD src0_sel:WORD_1
	v_add_f32_e32 v56, 0, v74
	v_pk_mul_f32 v[72:73], v[26:27], v[72:73]
	v_add_f32_e32 v56, v56, v75
	v_add_f32_e32 v72, v72, v82
	v_pk_add_f32 v[64:65], v[64:65], v[80:81] neg_lo:[0,1] neg_hi:[0,1]
	v_add_f32_e32 v56, v56, v68
	v_add_f32_e32 v72, v73, v72
	v_pk_fma_f32 v[64:65], v[34:35], v[64:65], v[80:81]
	v_add_f32_e32 v73, v56, v69
	v_cvt_f32_f16_sdwa v57, v66 dst_sel:DWORD dst_unused:UNUSED_PAD src0_sel:WORD_1
	v_cvt_f32_f16_e32 v56, v66
	v_cvt_f32_f16_sdwa v81, v70 dst_sel:DWORD dst_unused:UNUSED_PAD src0_sel:WORD_1
	v_cvt_f32_f16_e32 v80, v70
	v_cvt_f32_f16_e32 v70, v59
	v_cvt_f32_f16_e32 v66, v71
	v_cvt_f32_f16_sdwa v71, v59 dst_sel:DWORD dst_unused:UNUSED_PAD src0_sel:WORD_1
	v_pk_add_f32 v[80:81], v[80:81], v[56:57] neg_lo:[0,1] neg_hi:[0,1]
	v_cvt_f32_f16_e32 v82, v62
	v_pk_fma_f32 v[80:81], v[36:37], v[80:81], v[56:57]
	v_cvt_f32_f16_e32 v56, v58
	v_cvt_f32_f16_sdwa v57, v58 dst_sel:DWORD dst_unused:UNUSED_PAD src0_sel:WORD_1
	v_pk_add_f32 v[66:67], v[66:67], v[84:85] neg_lo:[0,1] neg_hi:[0,1]
	v_pk_add_f32 v[78:79], v[78:79], v[76:77] neg_lo:[0,1] neg_hi:[0,1]
	v_add_f32_e32 v58, v73, v56
	v_add_f32_e32 v58, v58, v57
	v_add_f32_e32 v58, v58, v70
	v_add_f32_e32 v58, v58, v71
	v_pk_fma_f32 v[66:67], v[38:39], v[66:67], v[84:85]
	v_add_f32_dpp v72, v72, v72 quad_perm:[1,0,3,2] row_mask:0xf bank_mask:0xf bound_ctrl:1
	v_add_f32_dpp v58, v58, v58 quad_perm:[1,0,3,2] row_mask:0xf bank_mask:0xf bound_ctrl:1
	v_pk_fma_f32 v[76:77], v[32:33], v[78:79], v[76:77]
	v_cvt_f32_f16_e32 v78, v60
	v_add_f32_dpp v58, v58, v58 quad_perm:[2,3,0,1] row_mask:0xf bank_mask:0xf bound_ctrl:1
	v_cvt_f32_f16_sdwa v79, v60 dst_sel:DWORD dst_unused:UNUSED_PAD src0_sel:WORD_1
	v_cvt_f32_f16_e32 v60, v61
	v_add_f32_dpp v58, v58, v58 row_half_mirror row_mask:0xf bank_mask:0xf bound_ctrl:1
	v_mul_f32_e32 v58, 0x3c800000, v58
	v_pk_add_f32 v[74:75], v[74:75], v[58:59] op_sel_hi:[1,0] neg_lo:[0,1] neg_hi:[0,1]
	v_pk_add_f32 v[68:69], v[68:69], v[58:59] op_sel_hi:[1,0] neg_lo:[0,1] neg_hi:[0,1]
	v_pk_mul_f32 v[84:85], v[74:75], v[74:75]
	v_pk_mul_f32 v[86:87], v[68:69], v[68:69]
	v_add_f32_e32 v62, v84, v85
	v_pk_add_f32 v[88:89], v[56:57], v[58:59] op_sel_hi:[1,0] neg_lo:[0,1] neg_hi:[0,1]
	v_add_f32_e32 v62, v86, v62
	v_pk_mul_f32 v[56:57], v[88:89], v[88:89]
	v_add_f32_e32 v62, v87, v62
	v_pk_add_f32 v[70:71], v[70:71], v[58:59] op_sel_hi:[1,0] neg_lo:[0,1] neg_hi:[0,1]
	v_add_f32_e32 v56, v56, v62
	v_pk_mul_f32 v[58:59], v[70:71], v[70:71]
	v_add_f32_e32 v56, v57, v56
	v_add_f32_e32 v56, v58, v56
	v_add_f32_e32 v56, v59, v56
	v_mov_b32_e32 v57, 0x3a27c5ac
	v_cvt_f32_f16_sdwa v61, v61 dst_sel:DWORD dst_unused:UNUSED_PAD src0_sel:WORD_1
	v_add_f32_dpp v56, v56, v56 quad_perm:[1,0,3,2] row_mask:0xf bank_mask:0xf bound_ctrl:1
	v_add_f32_dpp v72, v72, v72 quad_perm:[2,3,0,1] row_mask:0xf bank_mask:0xf bound_ctrl:1
	s_nop 0
	v_add_f32_dpp v56, v56, v56 quad_perm:[2,3,0,1] row_mask:0xf bank_mask:0xf bound_ctrl:1
	v_add_f32_dpp v72, v72, v72 row_half_mirror row_mask:0xf bank_mask:0xf bound_ctrl:1
	s_nop 0
	v_add_f32_dpp v56, v56, v56 row_half_mirror row_mask:0xf bank_mask:0xf bound_ctrl:1
	v_fmamk_f32 v56, v56, 0x3c800000, v57
	v_rsq_f32_e32 v62, v56
	s_nop 0
	v_pk_mul_f32 v[56:57], v[74:75], v[62:63] op_sel_hi:[1,0]
	v_pk_mul_f32 v[58:59], v[68:69], v[62:63] op_sel_hi:[1,0]
	v_pk_fma_f32 v[56:57], v[44:45], v[56:57], v[52:53]
	v_pk_fma_f32 v[58:59], v[46:47], v[58:59], v[54:55]
	v_pk_fma_f32 v[56:57], v[76:77], v[72:73], v[56:57] op_sel_hi:[1,0,1]
	v_pk_fma_f32 v[58:59], v[64:65], v[72:73], v[58:59] op_sel_hi:[1,0,1]
	v_pk_mul_f32 v[56:57], v[56:57], v[78:79]
	v_pk_mul_f32 v[58:59], v[58:59], v[60:61]
	v_cvt_pk_f16_f32 v56, v56, v57
	v_cvt_pk_f16_f32 v57, v58, v59
	v_pk_mul_f32 v[58:59], v[88:89], v[62:63] op_sel_hi:[1,0]
	v_pk_mul_f32 v[60:61], v[70:71], v[62:63] op_sel_hi:[1,0]
	v_cvt_f32_f16_e32 v62, v63
	v_cvt_f32_f16_sdwa v63, v63 dst_sel:DWORD dst_unused:UNUSED_PAD src0_sel:WORD_1
	v_pk_fma_f32 v[58:59], v[40:41], v[58:59], v[48:49]
	v_pk_fma_f32 v[60:61], v[42:43], v[60:61], v[50:51]
	v_pk_fma_f32 v[58:59], v[80:81], v[72:73], v[58:59] op_sel_hi:[1,0,1]
	v_pk_fma_f32 v[60:61], v[66:67], v[72:73], v[60:61] op_sel_hi:[1,0,1]
	v_pk_mul_f32 v[58:59], v[58:59], v[82:83]
	v_pk_mul_f32 v[60:61], v[60:61], v[62:63]
	v_cvt_pk_f16_f32 v58, v58, v59
	v_cvt_pk_f16_f32 v59, v60, v61
	global_store_dwordx4 v[94:95], v[56:59], off
	s_cbranch_scc1 .LBB0_1439
